# write-through stores for the gated-delta phase-1 outputs (q, k^T, u, w tiles)
# speedup vs baseline: 1.0031x; 1.0031x over previous
; DI unsigned char* WSP(const Params& P) { size_t z = 0; asm volatile("" : "+s"(z)); return P.ws + z; }
; DI void gdn_p1_item(const Params& P, int l, int it, float* lds) {
;     ...
;   f32x4 lreg[4];
;   {
;     const f32x4 Gi4 = *(const f32x4*)(sG + 16 * w + 4 * quad);
;     const f32x4 Bi4 = *(const f32x4*)(sBeta + 16 * w + 4 * quad);
;     u16* GA = (u16*)(WSP(P) + WS_GA) + ci * 4096;
; #pragma unroll
;     for (int nt = 0; nt < 4; ++nt) {
;       f32x4 aq = {0.f, 0.f, 0.f, 0.f}, ak = {0.f, 0.f, 0.f, 0.f};
; #pragma unroll
;       for (int ks = 0; ks < 2; ++ks) {
;         const bf16x8 fq = *(const bf16x8*)(sQb + (16 * w + r16) * 72 + ks * 32 + quad * 8);
;         const bf16x8 fk = *(const bf16x8*)(sKb + (16 * w + r16) * 72 + ks * 32 + quad * 8);
;         const bf16x8 fb = *(const bf16x8*)(sKb + (16 * nt + r16) * 72 + ks * 32 + quad * 8);
;         aq = __builtin_amdgcn_mfma_f32_16x16x32_bf16(fq, fb, aq, 0, 0, 0);
;         ak = __builtin_amdgcn_mfma_f32_16x16x32_bf16(fk, fb, ak, 0, 0, 0);
;       }
;       const int j = 16 * nt + r16;
;       const float Gj = sG[j];
; #pragma unroll
;       for (int jj = 0; jj < 4; ++jj) {
;         const int i = 16 * w + 4 * quad + jj;
;         const float dec = __expf(Gi4[jj] - Gj);
;         GA[i * 64 + j] = f2bf((j <= i) ? aq[jj] * dec : 0.f);
;         const float lv = (j < i) ? Bi4[jj] * ak[jj] * dec : 0.f;
;         sq[i * 65 + j] = lv;
;         lreg[nt][jj] = lv;
;       }
;     }
;   }
.LBB0_603:
	s_or_b64 exec, exec, s[4:5]
	v_ashrrev_i32_e32 v27, 6, v8
	v_and_b32_e32 v25, 15, v8
	v_lshlrev_b32_e32 v9, 4, v27
	v_and_b32_e32 v10, 48, v15
	s_movk_i32 s4, 0xffc0
	v_or_b32_e32 v11, v9, v25
	v_and_or_b32 v0, v8, s4, v10
	s_mov_b64 s[4:5], 0
	v_mad_u64_u32 v[12:13], s[6:7], v11, s54, v[10:11]
	s_waitcnt lgkmcnt(0)
	s_barrier
	ds_read_b128 v[4:7], v0 offset:49920
	ds_read_b128 v[0:3], v0 offset:50176
	ds_read_b128 v[16:19], v12 offset:50688
	v_mad_u32_u24 v29, v25, s54, v10
	ds_read_b128 v[20:23], v12 offset:59904
	ds_read_b128 v[30:33], v29 offset:59904
	v_lshlrev_b32_e32 v14, 2, v25
	ds_read_b128 v[34:37], v12 offset:50752
	ds_read_b128 v[38:41], v29 offset:59968
	ds_read_b128 v[42:45], v12 offset:59968
	ds_read_b32 v13, v14 offset:49920
	s_waitcnt lgkmcnt(4)
	v_mfma_f32_16x16x32_bf16 v[16:19], v[16:19], v[30:33], 0
	s_add_u32 s4, s70, s4
	s_waitcnt lgkmcnt(0)
	v_sub_f32_e32 v10, v4, v13
	v_mul_f32_e32 v10, 0x3fb8aa3b, v10
	v_mfma_f32_16x16x32_bf16 v[20:23], v[20:23], v[30:33], 0
	v_exp_f32_e32 v24, v10
	v_lshrrev_b32_e32 v28, 4, v15
	s_addc_u32 s5, s71, s5
	v_mfma_f32_16x16x32_bf16 v[16:19], v[34:37], v[38:41], v[16:19]
	s_lshl_b64 s[6:7], s[46:47], 12
	s_lshl_b64 s[8:9], s[46:47], 13
	s_add_u32 s4, s4, s8
	v_lshl_or_b32 v30, v28, 2, v9
	s_addc_u32 s5, s5, s9
	v_mfma_f32_16x16x32_bf16 v[20:23], v[42:45], v[38:41], v[20:23]
	v_lshlrev_b32_e32 v35, 6, v30
	s_add_u32 s10, s4, 0x17000000
	v_mul_f32_e32 v9, v16, v24
	v_or_b32_e32 v52, v35, v25
	s_addc_u32 s11, s5, 0
	v_cvt_pk_bf16_f32 v9, v9, s0
	v_cmp_gt_i32_e32 vcc, v25, v30
	v_ashrrev_i32_e32 v53, 31, v52
	v_lshl_add_u64 v[10:11], v[52:53], 1, s[10:11]
	v_cndmask_b32_e64 v9, v9, 0, vcc
	global_store_short v[10:11], v9, off
	v_mul_f32_e32 v9, v0, v20
	v_mul_f32_e32 v9, v9, v24
	v_cmp_lt_i32_e64 s[4:5], v25, v30
	v_or_b32_e32 v61, 3, v30
	v_lshlrev_b32_e32 v62, 6, v61
	v_cndmask_b32_e64 v31, 0, v9, s[4:5]
	v_sub_f32_e32 v9, v5, v13
	v_mul_f32_e32 v9, 0x3fb8aa3b, v9
	v_exp_f32_e32 v9, v9
	s_movk_i32 s4, 0x104
	v_mad_u64_u32 v[10:11], s[4:5], v30, s4, v[14:15]
	v_or_b32_e32 v11, 1, v30
	v_lshlrev_b32_e32 v24, 6, v11
	v_mul_f32_e32 v16, v17, v9
	v_or_b32_e32 v54, v24, v25
	v_cvt_pk_bf16_f32 v16, v16, s0
	v_cmp_le_i32_e64 s[4:5], v25, v11
	v_ashrrev_i32_e32 v55, 31, v54
	ds_write_b32 v10, v31
	v_cndmask_b32_e64 v20, 0, v16, s[4:5]
	v_lshl_add_u64 v[16:17], v[54:55], 1, s[10:11]
	global_store_short v[16:17], v20, off
	v_mul_f32_e32 v16, v1, v21
	v_mul_f32_e32 v9, v16, v9
	v_sub_f32_e32 v16, v6, v13
	v_mul_f32_e32 v16, 0x3fb8aa3b, v16
	v_exp_f32_e32 v20, v16
	v_cndmask_b32_e64 v32, v9, 0, vcc
	v_or_b32_e32 v9, 2, v30
	v_lshlrev_b32_e32 v60, 6, v9
	v_mul_f32_e32 v16, v18, v20
	v_or_b32_e32 v56, v60, v25
	v_sub_f32_e32 v13, v7, v13
	v_cvt_pk_bf16_f32 v16, v16, s0
	v_cmp_le_i32_e32 vcc, v25, v9
	v_ashrrev_i32_e32 v57, 31, v56
	v_mul_f32_e32 v13, 0x3fb8aa3b, v13
	v_cndmask_b32_e32 v18, 0, v16, vcc
	v_lshl_add_u64 v[16:17], v[56:57], 1, s[10:11]
	v_exp_f32_e32 v13, v13
	global_store_short v[16:17], v18, off
	v_mul_f32_e32 v16, v2, v22
	v_mul_f32_e32 v16, v16, v20
	v_cmp_lt_i32_e32 vcc, v25, v9
	ds_write_b32 v10, v32 offset:260
	v_or_b32_e32 v58, v62, v25
	v_cndmask_b32_e32 v33, 0, v16, vcc
	v_mul_f32_e32 v16, v3, v23
	v_mul_f32_e32 v16, v16, v13
	v_cmp_lt_i32_e32 vcc, v25, v61
	ds_write_b32 v10, v33 offset:520
	v_mul_f32_e32 v13, v19, v13
	v_cndmask_b32_e32 v34, 0, v16, vcc
	ds_write_b32 v10, v34 offset:780
	ds_read_b128 v[20:23], v12 offset:50688
	ds_read_b128 v[16:19], v12 offset:59904
	ds_read_b128 v[36:39], v29 offset:62208
	ds_read_b128 v[40:43], v12 offset:50752
	ds_read_b128 v[44:47], v29 offset:62272
	ds_read_b128 v[48:51], v12 offset:59968
	s_waitcnt lgkmcnt(3)
	v_mfma_f32_16x16x32_bf16 v[20:23], v[20:23], v[36:39], 0
	v_cvt_pk_bf16_f32 v13, v13, s0
	v_cmp_le_i32_e32 vcc, v25, v61
	v_ashrrev_i32_e32 v59, 31, v58
	v_mfma_f32_16x16x32_bf16 v[16:19], v[16:19], v[36:39], 0
	ds_read_b32 v38, v14 offset:49984
	v_cndmask_b32_e32 v13, 0, v13, vcc
	v_lshl_add_u64 v[36:37], v[58:59], 1, s[10:11]
	global_store_short v[36:37], v13, off
	s_waitcnt lgkmcnt(1)
	v_mfma_f32_16x16x32_bf16 v[16:19], v[48:51], v[44:47], v[16:19]
	s_waitcnt lgkmcnt(0)
	v_sub_f32_e32 v13, v4, v38
	v_mul_f32_e32 v13, 0x3fb8aa3b, v13
	v_exp_f32_e32 v13, v13
	v_mfma_f32_16x16x32_bf16 v[20:23], v[40:43], v[44:47], v[20:23]
	v_or_b32_e32 v59, 16, v25
	s_nop 1
	v_mul_f32_e32 v16, v0, v16
	v_cmp_lt_i32_e64 s[4:5], v59, v30
	v_ashrrev_i32_e32 v53, 31, v35
	v_cmp_gt_i32_e32 vcc, v59, v30
	s_nop 0
	v_mul_f32_e32 v20, v20, v13
	v_mul_f32_e32 v13, v16, v13
	v_sub_f32_e32 v16, v5, v38
	v_mul_f32_e32 v16, 0x3fb8aa3b, v16
	v_exp_f32_e32 v16, v16
	v_cndmask_b32_e64 v35, 0, v13, s[4:5]
	v_cvt_pk_bf16_f32 v20, v20, s0
	v_cmp_le_i32_e64 s[4:5], v59, v11
	v_mul_f32_e32 v13, v21, v16
	v_cvt_pk_bf16_f32 v13, v13, s0
	v_ashrrev_i32_e32 v55, 31, v24
	v_cndmask_b32_e64 v20, v20, 0, vcc
	v_lshl_add_u64 v[52:53], v[52:53], 1, s[10:11]
	v_cndmask_b32_e64 v13, 0, v13, s[4:5]
	v_lshl_add_u64 v[54:55], v[54:55], 1, s[10:11]
	global_store_short v[52:53], v20, off offset:32
	global_store_short v[54:55], v13, off offset:32
	v_mul_f32_e32 v13, v1, v17
	v_sub_f32_e32 v17, v6, v38
	v_mul_f32_e32 v17, 0x3fb8aa3b, v17
	v_exp_f32_e32 v17, v17
	v_mul_f32_e32 v13, v13, v16
	v_mul_f32_e32 v16, v2, v18
	v_cndmask_b32_e64 v64, v13, 0, vcc
	v_mul_f32_e32 v13, v22, v17
	v_mul_f32_e32 v16, v16, v17
	v_sub_f32_e32 v17, v7, v38
	v_mul_f32_e32 v17, 0x3fb8aa3b, v17
	v_exp_f32_e32 v20, v17
	v_cmp_lt_i32_e32 vcc, v59, v9
	ds_write_b32 v10, v35 offset:64
	ds_write_b32 v10, v64 offset:324
	v_cndmask_b32_e32 v65, 0, v16, vcc
	v_mul_f32_e32 v16, v3, v19
	v_mul_f32_e32 v16, v16, v20
	v_cmp_lt_i32_e32 vcc, v59, v61
	ds_write_b32 v10, v65 offset:584
	v_cvt_pk_bf16_f32 v13, v13, s0
	v_cndmask_b32_e32 v66, 0, v16, vcc
	ds_write_b32 v10, v66 offset:844
	ds_read_b128 v[16:19], v12 offset:50688
	v_cmp_le_i32_e32 vcc, v59, v9
	v_ashrrev_i32_e32 v57, 31, v60
	ds_read_b128 v[36:39], v12 offset:59904
	ds_read_b128 v[40:43], v29 offset:64512
	v_cndmask_b32_e32 v13, 0, v13, vcc
	v_lshl_add_u64 v[56:57], v[56:57], 1, s[10:11]
	global_store_short v[56:57], v13, off offset:32
	ds_read_b128 v[44:47], v12 offset:50752
	ds_read_b128 v[48:51], v29 offset:64576
	v_mul_f32_e32 v13, v23, v20
	ds_read_b128 v[20:23], v12 offset:59968
	ds_read_b32 v24, v14 offset:50048
	s_waitcnt lgkmcnt(4)
; DI unsigned char* WSP(const Params& P) { size_t z = 0; asm volatile("" : "+s"(z)); return P.ws + z; }
; DI unsigned pk2(float a, float b) { f32x2_t v = {a, b}; bf16x2_t r = __builtin_convertvector(v, bf16x2_t); return __builtin_bit_cast(unsigned, r); }
; DI void gdn_p1_item(const Params& P, int l, int it, float* lds) {
;     ...
;     for (int nt = 0; nt < 4; ++nt) {
;       f32x4 aq = {0.f, 0.f, 0.f, 0.f}, ak = {0.f, 0.f, 0.f, 0.f};
; #pragma unroll
;       for (int ks = 0; ks < 2; ++ks) {
;         const bf16x8 fq = *(const bf16x8*)(sQb + (16 * w + r16) * 72 + ks * 32 + quad * 8);
;         const bf16x8 fk = *(const bf16x8*)(sKb + (16 * w + r16) * 72 + ks * 32 + quad * 8);
;         const bf16x8 fb = *(const bf16x8*)(sKb + (16 * nt + r16) * 72 + ks * 32 + quad * 8);
;         aq = __builtin_amdgcn_mfma_f32_16x16x32_bf16(fq, fb, aq, 0, 0, 0);
;         ak = __builtin_amdgcn_mfma_f32_16x16x32_bf16(fk, fb, ak, 0, 0, 0);
;       }
;       const int j = 16 * nt + r16;
;       const float Gj = sG[j];
; #pragma unroll
;       for (int jj = 0; jj < 4; ++jj) {
;         const int i = 16 * w + 4 * quad + jj;
;         const float dec = __expf(Gi4[jj] - Gj);
;         GA[i * 64 + j] = f2bf((j <= i) ? aq[jj] * dec : 0.f);
;         const float lv = (j < i) ? Bi4[jj] * ak[jj] * dec : 0.f;
;         sq[i * 65 + j] = lv;
;         lreg[nt][jj] = lv;
;       }
;     }
;   }
;   {
;     u16* GQ = (u16*)(WSP(P) + WS_GQ) + ci * 4096;
; #pragma unroll
;     for (int q = 0; q < 2; ++q) { const int c = tid + 256 * q, row = c >> 3, ch = c & 7; *(uint4*)(GQ + row * 64 + ch * 8) = *(const uint4*)(sQb + row * 72 + ch * 8); }
;     const int i = tid >> 2, j0 = (tid & 3) * 16;
;     u16* GK = (u16*)(WSP(P) + WS_GK) + ci * 4096 + i * 64 + j0;
;     unsigned ok[8];
; #pragma unroll
;     for (int q = 0; q < 8; ++q) ok[q] = pk2(sk[(j0 + 2 * q) * 65 + i], sk[(j0 + 2 * q + 1) * 65 + i]);
;     ((uint4*)GK)[0] = make_uint4(ok[0], ok[1], ok[2], ok[3]); ((uint4*)GK)[1] = make_uint4(ok[4], ok[5], ok[6], ok[7]);
	v_mfma_f32_16x16x32_bf16 v[16:19], v[16:19], v[40:43], 0
	v_cvt_pk_bf16_f32 v13, v13, s0
	v_cmp_le_i32_e32 vcc, v59, v61
	v_ashrrev_i32_e32 v59, 31, v62
	v_mfma_f32_16x16x32_bf16 v[36:39], v[36:39], v[40:43], 0
	s_waitcnt lgkmcnt(0)
	v_sub_f32_e32 v40, v4, v24
	v_mul_f32_e32 v40, 0x3fb8aa3b, v40
	v_exp_f32_e32 v40, v40
	v_mfma_f32_16x16x32_bf16 v[16:19], v[44:47], v[48:51], v[16:19]
	v_cndmask_b32_e32 v13, 0, v13, vcc
	v_lshl_add_u64 v[58:59], v[58:59], 1, s[10:11]
	global_store_short v[58:59], v13, off offset:32
	v_mfma_f32_16x16x32_bf16 v[20:23], v[20:23], v[48:51], v[36:39]
	v_or_b32_e32 v13, 32, v25
	s_nop 2
	v_mul_f32_e32 v16, v16, v40
	v_cvt_pk_bf16_f32 v16, v16, s0
	v_cmp_gt_i32_e32 vcc, v13, v30
	v_cmp_lt_i32_e64 s[4:5], v13, v30
	v_add_u32_e32 v63, 0x900, v29
	v_cndmask_b32_e64 v16, v16, 0, vcc
	global_store_short v[52:53], v16, off offset:64
	v_mul_f32_e32 v16, v0, v20
	v_sub_f32_e32 v20, v5, v24
	v_mul_f32_e32 v20, 0x3fb8aa3b, v20
	v_exp_f32_e32 v20, v20
	v_mul_f32_e32 v16, v16, v40
	v_cndmask_b32_e64 v60, 0, v16, s[4:5]
	v_cmp_le_i32_e64 s[4:5], v13, v11
	v_mul_f32_e32 v16, v17, v20
	v_cvt_pk_bf16_f32 v16, v16, s0
	v_cndmask_b32_e64 v16, 0, v16, s[4:5]
	v_sub_f32_e32 v17, v6, v24
	global_store_short v[54:55], v16, off offset:64
	v_mul_f32_e32 v16, v1, v21
	v_mul_f32_e32 v17, 0x3fb8aa3b, v17
	v_mul_f32_e32 v16, v16, v20
	v_exp_f32_e32 v17, v17
	v_sub_f32_e32 v20, v7, v24
	v_mul_f32_e32 v20, 0x3fb8aa3b, v20
	v_exp_f32_e32 v24, v20
	v_cndmask_b32_e64 v62, v16, 0, vcc
	v_mul_f32_e32 v16, v2, v22
	v_mul_f32_e32 v16, v16, v17
	v_cmp_lt_i32_e32 vcc, v13, v9
	ds_write_b32 v10, v60 offset:128
	ds_write_b32 v10, v62 offset:388
	v_cndmask_b32_e32 v67, 0, v16, vcc
	v_mul_f32_e32 v16, v3, v23
	v_mul_f32_e32 v16, v16, v24
	v_cmp_lt_i32_e32 vcc, v13, v61
	ds_write_b32 v10, v67 offset:648
	v_mul_f32_e32 v24, v19, v24
	v_cndmask_b32_e32 v68, 0, v16, vcc
	ds_write_b32 v10, v68 offset:908
	ds_read_b128 v[20:23], v12 offset:50688
	v_mul_f32_e32 v16, v18, v17
	v_cvt_pk_bf16_f32 v16, v16, s0
	v_cmp_le_i32_e32 vcc, v13, v9
	ds_read_b128 v[36:39], v12 offset:59904
	ds_read_b128 v[40:43], v63 offset:64512
	v_cndmask_b32_e32 v16, 0, v16, vcc
	ds_read_b128 v[44:47], v12 offset:50752
	ds_read_b128 v[48:51], v63 offset:64576
	global_store_short v[56:57], v16, off offset:64
	ds_read_b128 v[16:19], v12 offset:59968
	ds_read_b32 v12, v14 offset:50112
	s_waitcnt lgkmcnt(4)
	v_mfma_f32_16x16x32_bf16 v[36:39], v[36:39], v[40:43], 0
	v_cvt_pk_bf16_f32 v14, v24, s0
	v_cmp_le_i32_e32 vcc, v13, v61
	v_lshl_add_u32 v26, v15, 2, v26
	v_mfma_f32_16x16x32_bf16 v[20:23], v[20:23], v[40:43], 0
	s_waitcnt lgkmcnt(0)
	v_sub_f32_e32 v4, v4, v12
	v_mul_f32_e32 v4, 0x3fb8aa3b, v4
	v_exp_f32_e32 v4, v4
	v_mfma_f32_16x16x32_bf16 v[16:19], v[16:19], v[48:51], v[36:39]
	v_cndmask_b32_e32 v13, 0, v14, vcc
	global_store_short v[58:59], v13, off offset:64
	v_or_b32_e32 v13, 48, v25
	v_mfma_f32_16x16x32_bf16 v[20:23], v[44:47], v[48:51], v[20:23]
	v_cmp_lt_i32_e64 s[4:5], v13, v30
	s_nop 2
	v_mul_f32_e32 v0, v0, v16
	v_mul_f32_e32 v0, v0, v4
	v_cndmask_b32_e64 v37, 0, v0, s[4:5]
	v_cmp_gt_i32_e32 vcc, v13, v30
	v_mul_f32_e32 v14, v20, v4
	v_sub_f32_e32 v4, v5, v12
	v_mul_f32_e32 v4, 0x3fb8aa3b, v4
	v_exp_f32_e32 v4, v4
	v_cvt_pk_bf16_f32 v14, v14, s0
	v_cmp_le_i32_e64 s[4:5], v13, v11
	v_cndmask_b32_e64 v14, v14, 0, vcc
	v_mul_f32_e32 v0, v21, v4
	v_cvt_pk_bf16_f32 v0, v0, s0
	v_cndmask_b32_e64 v0, 0, v0, s[4:5]
	global_store_short v[52:53], v14, off offset:96
	global_store_short v[54:55], v0, off offset:96
	v_mul_f32_e32 v0, v1, v17
	v_sub_f32_e32 v1, v6, v12
	v_mul_f32_e32 v1, 0x3fb8aa3b, v1
	v_exp_f32_e32 v1, v1
	v_mul_f32_e32 v0, v0, v4
	v_cndmask_b32_e64 v44, v0, 0, vcc
	v_cmp_le_i32_e32 vcc, v13, v9
	v_mul_f32_e32 v0, v22, v1
	v_cvt_pk_bf16_f32 v0, v0, s0
	v_cndmask_b32_e32 v0, 0, v0, vcc
	global_store_short v[56:57], v0, off offset:96
	v_mul_f32_e32 v0, v2, v18
	v_mul_f32_e32 v0, v0, v1
	v_sub_f32_e32 v1, v7, v12
	v_mul_f32_e32 v1, 0x3fb8aa3b, v1
	v_exp_f32_e32 v1, v1
	v_cmp_lt_i32_e32 vcc, v13, v9
	s_mov_b64 s[4:5], 0
	ds_write_b32 v10, v37 offset:192
	v_cndmask_b32_e32 v45, 0, v0, vcc
	v_mul_f32_e32 v0, v23, v1
	v_cvt_pk_bf16_f32 v0, v0, s0
	v_cmp_le_i32_e32 vcc, v13, v61
	ds_write_b32 v10, v44 offset:452
	ds_write_b32 v10, v45 offset:712
	v_cndmask_b32_e32 v0, 0, v0, vcc
	global_store_short v[58:59], v0, off offset:96
	v_mul_f32_e32 v0, v3, v19
	v_mul_f32_e32 v0, v0, v1
	v_cmp_lt_i32_e32 vcc, v13, v61
	v_lshlrev_b32_e32 v9, 4, v8
	v_and_b32_e32 v162, 0x70, v9
	v_cndmask_b32_e32 v46, 0, v0, vcc
	ds_write_b32 v10, v46 offset:972
	s_add_u32 s4, s70, s4
	s_addc_u32 s5, s71, s5
	s_add_u32 s4, s4, s8
	s_addc_u32 s5, s5, s9
	v_lshl_add_u64 v[0:1], s[4:5], 0, v[162:163]
	s_mov_b64 s[4:5], 0x13000000
	v_ashrrev_i32_e32 v2, 3, v8
	v_lshl_add_u64 v[10:11], v[0:1], 0, s[4:5]
	v_mad_u64_u32 v[0:1], s[4:5], v2, s54, v[162:163]
	v_lshlrev_b32_e32 v2, 6, v2
	v_ashrrev_i32_e32 v3, 31, v2
	v_lshl_add_u64 v[12:13], v[2:3], 1, v[10:11]
	ds_read_b128 v[0:3], v0 offset:50688
	v_add_u32_e32 v4, 0x100, v8
	v_ashrrev_i32_e32 v14, 3, v4
	v_mad_u64_u32 v[4:5], s[4:5], v14, s54, v[162:163]
	ds_read_b128 v[4:7], v4 offset:50688
	s_waitcnt lgkmcnt(1)
	global_store_dwordx4 v[12:13], v[0:3], off sc1
	s_mov_b64 s[4:5], 0
	s_nop 0
	v_lshlrev_b32_e32 v0, 6, v14
	v_ashrrev_i32_e32 v1, 31, v0
	v_lshl_add_u64 v[0:1], v[0:1], 1, v[10:11]
	s_waitcnt lgkmcnt(0)
	global_store_dwordx4 v[0:1], v[4:7], off sc1
	s_add_u32 s4, s70, s4
	s_addc_u32 s5, s71, s5
	v_and_b32_e32 v4, 48, v9
	v_and_b32_e32 v9, -4, v8
	v_mul_u32_u24_e32 v0, 0x41, v4
	v_lshl_add_u32 v14, v0, 2, v9
	v_add_u32_e32 v0, 0x4000, v14
	v_add_u32_e32 v2, 0x4200, v14
	ds_read2_b32 v[0:1], v0 offset0:64 offset1:129
	ds_read2_b32 v[2:3], v2 offset0:66 offset1:131
	v_add_u32_e32 v6, 0x4400, v14
	ds_read2_b32 v[10:11], v6 offset0:68 offset1:133
	v_ashrrev_i32_e32 v5, 2, v8
	s_waitcnt lgkmcnt(2)
; DI unsigned char* WSP(const Params& P) { size_t z = 0; asm volatile("" : "+s"(z)); return P.ws + z; }
; DI unsigned pk2(float a, float b) { f32x2_t v = {a, b}; bf16x2_t r = __builtin_convertvector(v, bf16x2_t); return __builtin_bit_cast(unsigned, r); }
; DI void gdn_p1_item(const Params& P, int l, int it, float* lds) {
;     ...
;     const int i = tid >> 2, j0 = (tid & 3) * 16;
;     u16* GK = (u16*)(WSP(P) + WS_GK) + ci * 4096 + i * 64 + j0;
;     unsigned ok[8];
; #pragma unroll
;     for (int q = 0; q < 8; ++q) ok[q] = pk2(sk[(j0 + 2 * q) * 65 + i], sk[(j0 + 2 * q + 1) * 65 + i]);
;     ((uint4*)GK)[0] = make_uint4(ok[0], ok[1], ok[2], ok[3]); ((uint4*)GK)[1] = make_uint4(ok[4], ok[5], ok[6], ok[7]);
;   }
;   __syncthreads();
;   u16* sLb = sQb;
;   u16* sXT = sKb;
;   {
;     const int i = tid >> 2, j0 = (tid & 3) * 16;
;     const float bi = sBeta[i], eg = __expf(sG[i]);
; #pragma unroll
;     for (int jj = 0; jj < 16; ++jj) { sv[i * 65 + j0 + jj] *= bi; sk[i * 65 + j0 + jj] *= bi * eg; }
; #pragma unroll
;     for (int nt = 0; nt < 4; ++nt)
; #pragma unroll
;       for (int jj = 0; jj < 4; ++jj) sLb[(16 * w + 4 * quad + jj) * 72 + 16 * nt + r16] = f2bf(lreg[nt][jj]);
;   }
;   __syncthreads();
	v_cvt_pk_bf16_f32 v0, v0, v1
	s_waitcnt lgkmcnt(1)
	v_cvt_pk_bf16_f32 v1, v2, v3
	v_add_u32_e32 v3, 0x4600, v14
	s_waitcnt lgkmcnt(0)
	v_cvt_pk_bf16_f32 v2, v10, v11
	ds_read2_b32 v[10:11], v3 offset0:70 offset1:135
	v_add_u32_e32 v3, 0x4800, v14
	ds_read2_b32 v[12:13], v3 offset0:72 offset1:137
	v_add_u32_e32 v3, 0x4a00, v14
	ds_read2_b32 v[16:17], v3 offset0:74 offset1:139
	v_add_u32_e32 v3, 0x4c00, v14
	ds_read2_b32 v[18:19], v3 offset0:76 offset1:141
	v_lshlrev_b32_e32 v6, 6, v5
	s_add_u32 s4, s4, s8
	v_ashrrev_i32_e32 v7, 31, v6
	v_add_u32_e32 v3, 0x4e00, v14
	s_addc_u32 s5, s5, s9
	ds_read2_b32 v[20:21], v3 offset0:78 offset1:143
	s_waitcnt lgkmcnt(4)
	v_cvt_pk_bf16_f32 v3, v10, v11
	s_waitcnt lgkmcnt(2)
	v_cvt_pk_bf16_f32 v11, v16, v17
	v_lshl_add_u64 v[16:17], v[6:7], 1, s[4:5]
	v_lshlrev_b32_e32 v162, 1, v4
	v_lshl_add_u64 v[16:17], v[16:17], 0, v[162:163]
	s_mov_b64 s[4:5], 0x14000000
	v_cvt_pk_bf16_f32 v10, v12, v13
	s_waitcnt lgkmcnt(1)
	v_cvt_pk_bf16_f32 v12, v18, v19
	v_lshl_add_u64 v[18:19], v[16:17], 0, s[4:5]
	s_brev_b32 s4, 40
	v_add_co_u32_e32 v16, vcc, s4, v16
	s_waitcnt lgkmcnt(0)
	v_cvt_pk_bf16_f32 v13, v20, v21
	v_addc_co_u32_e32 v17, vcc, 0, v17, vcc
	global_store_dwordx4 v[16:17], v[0:3], off sc1
	global_store_dwordx4 v[18:19], v[10:13], off offset:16 sc1
	s_barrier
	ds_read2st64_b32 v[0:1], v9 offset0:195 offset1:196
	v_lshl_add_u32 v2, v5, 6, v5
	v_add_lshl_u32 v5, v2, v4, 2
	v_add_u32_e32 v24, 0x8200, v5
	ds_read2_b32 v[2:3], v24 offset1:1
	s_waitcnt lgkmcnt(1)
	v_mul_f32_e32 v0, 0x3fb8aa3b, v0
	v_exp_f32_e32 v0, v0
	v_add_u32_e32 v21, 0x4100, v5
	v_add_u32_e32 v23, 0x8208, v5
	v_add_u32_e32 v20, 0x4108, v5
	ds_read2_b32 v[10:11], v21 offset1:1
	ds_read2_b32 v[12:13], v23 offset1:1
	ds_read2_b32 v[16:17], v20 offset1:1
	v_mov_b32_e32 v36, v1
	v_mul_f32_e32 v0, v1, v0
	s_waitcnt lgkmcnt(3)
	v_pk_mul_f32 v[2:3], v[36:37], v[2:3] op_sel_hi:[0,1]
	ds_write2_b32 v24, v2, v3 offset1:1
	s_waitcnt lgkmcnt(3)
	v_pk_mul_f32 v[2:3], v[0:1], v[10:11] op_sel_hi:[0,1]
	ds_write2_b32 v21, v2, v3 offset1:1
	s_waitcnt lgkmcnt(3)
	v_pk_mul_f32 v[2:3], v[36:37], v[12:13] op_sel_hi:[0,1]
	ds_write2_b32 v23, v2, v3 offset1:1
	s_waitcnt lgkmcnt(3)
	v_pk_mul_f32 v[2:3], v[0:1], v[16:17] op_sel_hi:[0,1]
	v_add_u32_e32 v22, 0x8210, v5
	ds_write2_b32 v20, v2, v3 offset1:1
	ds_read2_b32 v[2:3], v22 offset1:1
	v_add_u32_e32 v19, 0x4110, v5
	v_add_u32_e32 v18, 0x8218, v5
	v_add_u32_e32 v14, 0x4118, v5
	ds_read2_b32 v[10:11], v19 offset1:1
	ds_read2_b32 v[12:13], v18 offset1:1
	ds_read2_b32 v[16:17], v14 offset1:1
	s_waitcnt lgkmcnt(3)
	v_pk_mul_f32 v[2:3], v[36:37], v[2:3] op_sel_hi:[0,1]
	ds_write2_b32 v22, v2, v3 offset1:1
	s_waitcnt lgkmcnt(3)
	v_pk_mul_f32 v[2:3], v[0:1], v[10:11] op_sel_hi:[0,1]
	ds_write2_b32 v19, v2, v3 offset1:1
	s_waitcnt lgkmcnt(3)
	v_pk_mul_f32 v[2:3], v[36:37], v[12:13] op_sel_hi:[0,1]
	ds_write2_b32 v18, v2, v3 offset1:1
	s_waitcnt lgkmcnt(3)
	v_pk_mul_f32 v[2:3], v[0:1], v[16:17] op_sel_hi:[0,1]
	v_add_u32_e32 v17, 0x8220, v5
	ds_write2_b32 v14, v2, v3 offset1:1
	ds_read2_b32 v[2:3], v17 offset1:1
	v_add_u32_e32 v13, 0x4120, v5
	v_add_u32_e32 v16, 0x8228, v5
	v_add_u32_e32 v10, 0x4128, v5
	ds_read2_b32 v[38:39], v13 offset1:1
	ds_read2_b32 v[40:41], v16 offset1:1
	ds_read2_b32 v[42:43], v10 offset1:1
	s_waitcnt lgkmcnt(3)
	v_pk_mul_f32 v[2:3], v[36:37], v[2:3] op_sel_hi:[0,1]
	ds_write2_b32 v17, v2, v3 offset1:1
	s_waitcnt lgkmcnt(3)
	v_pk_mul_f32 v[2:3], v[0:1], v[38:39] op_sel_hi:[0,1]
	ds_write2_b32 v13, v2, v3 offset1:1
	s_waitcnt lgkmcnt(3)
	v_pk_mul_f32 v[2:3], v[36:37], v[40:41] op_sel_hi:[0,1]
	ds_write2_b32 v16, v2, v3 offset1:1
	s_waitcnt lgkmcnt(3)
	v_pk_mul_f32 v[2:3], v[0:1], v[42:43] op_sel_hi:[0,1]
	v_add_u32_e32 v12, 0x8230, v5
	ds_write2_b32 v10, v2, v3 offset1:1
	v_add_u32_e32 v9, 0x4130, v5
	ds_read2_b32 v[2:3], v12 offset1:1
	v_add_u32_e32 v11, 0x8238, v5
	v_add_u32_e32 v5, 0x4138, v5
	ds_read2_b32 v[38:39], v9 offset1:1
	ds_read2_b32 v[40:41], v11 offset1:1
	ds_read2_b32 v[42:43], v5 offset1:1
	s_mov_b32 s8, 3
	s_waitcnt lgkmcnt(3)
	v_pk_mul_f32 v[2:3], v[36:37], v[2:3] op_sel_hi:[0,1]
	ds_write2_b32 v12, v2, v3 offset1:1
	s_waitcnt lgkmcnt(3)
	v_pk_mul_f32 v[2:3], v[0:1], v[38:39] op_sel_hi:[0,1]
	s_waitcnt lgkmcnt(1)
	v_pk_mul_f32 v[0:1], v[0:1], v[42:43] op_sel_hi:[0,1]
	ds_write2_b32 v5, v0, v1 offset1:1
	v_mul_lo_u32 v1, v30, s54
	v_cvt_pk_bf16_f32 v0, v31, s0
	v_lshl_or_b32 v1, v25, 1, v1
	ds_write_b16 v1, v0 offset:50688
	v_cvt_pk_bf16_f32 v0, v32, s0
	ds_write_b16 v1, v0 offset:50832
	v_cvt_pk_bf16_f32 v0, v33, s0
	ds_write_b16 v1, v0 offset:50976
	v_cvt_pk_bf16_f32 v0, v34, s0
	ds_write_b16 v1, v0 offset:51120
	v_cvt_pk_bf16_f32 v0, v35, s0
	ds_write_b16 v1, v0 offset:50720
	v_cvt_pk_bf16_f32 v0, v64, s0
	ds_write_b16 v1, v0 offset:50864
	v_cvt_pk_bf16_f32 v0, v65, s0
	ds_write_b16 v1, v0 offset:51008
	v_cvt_pk_bf16_f32 v0, v66, s0
	ds_write_b16 v1, v0 offset:51152
	v_cvt_pk_bf16_f32 v0, v60, s0
	ds_write_b16 v1, v0 offset:50752
	v_cvt_pk_bf16_f32 v0, v62, s0
	ds_write_b16 v1, v0 offset:50896
	v_cvt_pk_bf16_f32 v0, v67, s0
	ds_write_b16 v1, v0 offset:51040
	v_cvt_pk_bf16_f32 v0, v68, s0
	ds_write_b16 v1, v0 offset:51184
	v_cvt_pk_bf16_f32 v0, v37, s0
	ds_write_b16 v1, v0 offset:50784
	v_cvt_pk_bf16_f32 v0, v44, s0
	ds_write_b16 v1, v0 offset:50928
	v_cvt_pk_bf16_f32 v0, v45, s0
	ds_write_b16 v1, v0 offset:51072
	v_cvt_pk_bf16_f32 v0, v46, s0
	ds_write2_b32 v9, v2, v3 offset1:1
	v_pk_mul_f32 v[2:3], v[36:37], v[40:41] op_sel_hi:[0,1]
	ds_write_b16 v1, v0 offset:51216
	v_lshl_or_b32 v0, v27, 5, v25
	v_lshlrev_b16_e32 v27, 5, v27
	ds_write2_b32 v11, v2, v3 offset1:1
	v_mul_lo_u32 v30, v8, 48
	v_mul_lo_u32 v2, v0, 48
	v_cmp_gt_i32_e64 s[4:5], 64, v0
	v_or_b32_e32 v0, 16, v0
	v_bitop3_b16 v8, v27, v8, 15 bitop3:0xf8
	v_cndmask_b32_e64 v3, v195, v199, s[4:5]
	v_cmp_gt_i32_e64 s[4:5], 64, v0
	v_and_b32_e32 v8, 47, v8
	v_lshlrev_b32_e32 v8, 2, v8
	v_cndmask_b32_e64 v0, v195, v199, s[4:5]
	s_movk_i32 s4, 0x410
	v_mad_u32_u24 v8, v28, s4, v8
	s_movk_i32 s5, 0x1040
	v_add3_u32 v8, v3, v8, s5
	v_bitop3_b16 v3, v27, 16, v25 bitop3:0xfe
	v_and_b32_e32 v3, 63, v3
	v_lshlrev_b32_e32 v3, 2, v3
	v_and_b32_e32 v1, 16, v15
	v_mad_u32_u24 v3, v28, s4, v3
	s_mov_b32 s9, 0
	v_cmp_lt_u32_e32 vcc, 31, v15
	v_add_u32_e32 v15, 0xcf00, v29
	v_add3_u32 v25, v0, v3, s5
	v_add_u32_e32 v27, v1, v2
	s_waitcnt lgkmcnt(0)
	s_barrier
	s_branch .LBB0_605

; DI unsigned char* WSP(const Params& P) { size_t z = 0; asm volatile("" : "+s"(z)); return P.ws + z; }
; DI unsigned pk2(float a, float b) { f32x2_t v = {a, b}; bf16x2_t r = __builtin_convertvector(v, bf16x2_t); return __builtin_bit_cast(unsigned, r); }
; DI void gdn_p1_item(const Params& P, int l, int it, float* lds) {
;     ...
;   {
;     const int i = tid >> 2, j0 = (tid & 3) * 16;
;     u16* GU = (u16*)(WSP(P) + WS_GU) + ci * 4096 + i * 64 + j0;
;     u16* GW = (u16*)(WSP(P) + WS_GW) + ci * 4096 + i * 64 + j0;
;     unsigned ou[8], ow[8];
; #pragma unroll
;     for (int q = 0; q < 8; ++q) {
;       ou[q] = pk2(sv[i * 65 + j0 + 2 * q], sv[i * 65 + j0 + 2 * q + 1]);
;       ow[q] = pk2(sk[i * 65 + j0 + 2 * q], sk[i * 65 + j0 + 2 * q + 1]);
;     }
;     ((uint4*)GU)[0] = make_uint4(ou[0], ou[1], ou[2], ou[3]); ((uint4*)GU)[1] = make_uint4(ou[4], ou[5], ou[6], ou[7]);
;     ((uint4*)GW)[0] = make_uint4(ow[0], ow[1], ow[2], ow[3]); ((uint4*)GW)[1] = make_uint4(ow[4], ow[5], ow[6], ow[7]);
;   }
.LBB0_612:
	s_mov_b64 s[0:1], 0
	s_mov_b64 s[4:5], 0
	ds_read2_b32 v[0:1], v24 offset1:1
	ds_read2_b32 v[2:3], v21 offset1:1
	ds_read2_b32 v[14:15], v14 offset1:1
	ds_read2_b32 v[8:9], v9 offset1:1
	s_add_u32 s4, s70, s4
	s_waitcnt lgkmcnt(3)
	v_cvt_pk_bf16_f32 v0, v0, v1
	s_waitcnt lgkmcnt(2)
	v_cvt_pk_bf16_f32 v24, v2, v3
	ds_read2_b32 v[2:3], v23 offset1:1
	s_addc_u32 s5, s71, s5
	s_add_u32 s8, s70, s0
	s_addc_u32 s9, s71, s1
	s_lshl_b64 s[0:1], s[6:7], 1
	s_waitcnt lgkmcnt(0)
	v_cvt_pk_bf16_f32 v1, v2, v3
	ds_read2_b32 v[2:3], v20 offset1:1
	ds_read2_b32 v[20:21], v19 offset1:1
	ds_read2_b32 v[18:19], v18 offset1:1
	s_add_u32 s4, s4, s0
	s_addc_u32 s5, s5, s1
	s_waitcnt lgkmcnt(2)
	v_cvt_pk_bf16_f32 v25, v2, v3
	ds_read2_b32 v[2:3], v22 offset1:1
	s_waitcnt lgkmcnt(2)
	v_cvt_pk_bf16_f32 v26, v20, v21
	s_add_u32 s0, s8, s0
	v_lshlrev_b64 v[6:7], 1, v[6:7]
	s_addc_u32 s1, s9, s1
	s_waitcnt lgkmcnt(0)
	v_cvt_pk_bf16_f32 v2, v2, v3
	v_cvt_pk_bf16_f32 v3, v18, v19
	ds_read2_b32 v[18:19], v13 offset1:1
	v_cvt_pk_bf16_f32 v27, v14, v15
	ds_read2_b32 v[14:15], v17 offset1:1
	ds_read2_b32 v[16:17], v16 offset1:1
	v_cvt_pk_bf16_f32 v20, v8, v9
	ds_read2_b32 v[8:9], v11 offset1:1
	v_lshlrev_b32_e32 v162, 1, v4
	s_waitcnt lgkmcnt(2)
	v_cvt_pk_bf16_f32 v14, v14, v15
	s_waitcnt lgkmcnt(1)
	v_cvt_pk_bf16_f32 v15, v16, v17
	ds_read2_b32 v[16:17], v10 offset1:1
	v_cvt_pk_bf16_f32 v18, v18, v19
	ds_read2_b32 v[12:13], v12 offset1:1
	s_waitcnt lgkmcnt(1)
	v_cvt_pk_bf16_f32 v19, v16, v17
	v_cvt_pk_bf16_f32 v17, v8, v9
	ds_read2_b32 v[8:9], v5 offset1:1
	s_waitcnt lgkmcnt(1)
	v_cvt_pk_bf16_f32 v16, v12, v13
	s_waitcnt lgkmcnt(0)
	v_cvt_pk_bf16_f32 v21, v8, v9
	v_lshl_add_u64 v[8:9], s[4:5], 0, v[6:7]
	v_lshl_add_u64 v[6:7], s[0:1], 0, v[6:7]
	v_lshl_add_u64 v[6:7], v[6:7], 0, v[162:163]
	s_mov_b64 s[0:1], 0x15000000
	v_lshl_add_u64 v[10:11], v[6:7], 0, s[0:1]
	s_mov_b32 s0, 0x15000000
	v_add_co_u32_e32 v6, vcc, s0, v6
	v_lshl_add_u64 v[4:5], v[8:9], 0, v[162:163]
	s_nop 0
	v_addc_co_u32_e32 v7, vcc, 0, v7, vcc
	global_store_dwordx4 v[6:7], v[0:3], off sc1
	global_store_dwordx4 v[10:11], v[14:17], off offset:16 sc1
	s_mov_b64 s[4:5], 0x16000000
	v_add_co_u32_e32 v0, vcc, 0x16000000, v4
	v_lshl_add_u64 v[8:9], v[4:5], 0, s[4:5]
	s_nop 0
	v_addc_co_u32_e32 v1, vcc, 0, v5, vcc
	global_store_dwordx4 v[0:1], v[24:27], off sc1
	global_store_dwordx4 v[8:9], v[18:21], off offset:16 sc1
